# rs phase: second task's 64KB retention state prefetched into spare VGPRs during the first task (on top of rows0 hoist version)
# speedup vs baseline: 1.0074x; 1.0074x over previous
.LBB0_669:
	v_readlane_b32 s2, v255, 19
	v_readlane_b32 s0, v254, 1
	v_readlane_b32 s3, v255, 20
	v_readlane_b32 s1, v254, 2
	s_andn2_b64 vcc, exec, s[2:3]
	s_cbranch_vccnz .LBB0_694
	s_load_dwordx4 s[44:47], s[0:1], 0x70
	s_load_dwordx4 s[48:51], s[0:1], 0x20
	s_nop 0
	s_load_dwordx2 s[0:1], s[0:1], 0x60
	s_lshl_b32 s2, s27, 7
	v_readlane_b32 s8, v254, 0
	s_waitcnt lgkmcnt(0)
	s_add_u32 s3, s44, 0x4cf0000
	s_addc_u32 s4, s45, 0
	s_lshl_b32 s22, s27, 9
	s_lshl_b32 s5, s27, 17
	s_lshl_b64 s[6:7], s[22:23], 2
	s_add_u32 s10, s0, s6
	s_addc_u32 s11, s1, s7
	s_add_u32 s6, s44, 0xccf0000
	s_addc_u32 s7, s45, 0
	s_mov_b32 s92, 0
	s_mov_b32 s94, s62
	s_mov_b32 s95, 0
	s_lshl_b64 s[94:95], s[94:95], 16
	s_branch .LBB0_673

.LBB0_672:
	s_cmp_eq_u32 s92, 1
	s_cselect_b32 s92, 2, 0
	s_add_i32 s8, s8, s62
	s_cmpk_gt_i32 s8, 0x1ff
	s_barrier
	s_cbranch_scc1 .LBB0_694
.LBB0_673:
	s_mov_b64 s[20:21], s[46:47]
	s_ashr_i32 s9, s8, 2
	s_and_b32 s26, s8, 3
	s_add_u32 s0, s20, 0x6801000
	s_addc_u32 s1, s21, 0
	s_lshl_b32 s12, s9, 3
	s_ashr_i32 s13, s12, 31
	s_add_u32 s12, s12, 0x4000
	s_addc_u32 s13, s13, 0
	s_add_i32 s9, s9, s2
	s_lshl_b32 s16, s9, 2
	s_or_b32 s24, s16, s26
	v_mov_b32_e32 v84, v224
	s_ashr_i32 s25, s24, 31
	s_lshl_b64 s[16:17], s[24:25], 16
	s_waitcnt vmcnt(10)
	v_lshlrev_b32_e32 v0, 2, v84
	s_add_u32 s16, s48, s16
	v_and_b32_e32 v2, 0x7c, v0
	v_ashrrev_i32_e32 v100, 5, v84
	s_addc_u32 s17, s49, s17
	v_lshlrev_b32_e32 v102, 10, v100
	v_lshlrev_b32_e32 v196, 2, v2
	v_ashrrev_i32_e32 v96, 6, v84
	v_lshl_add_u64 v[0:1], s[16:17], 0, v[196:197]
	v_ashrrev_i32_e32 v103, 31, v102
	v_lshl_add_u64 v[0:1], v[102:103], 2, v[0:1]
	v_ashrrev_i32_e32 v97, 31, v96
	v_lshl_add_u64 v[210:211], v[0:1], 0, s[94:95]
	s_cmp_eq_u32 s92, 2
	s_cbranch_scc1 .Lrs_skip_s0
	global_load_dwordx4 v[48:51], v[0:1], off nt
	global_load_dwordx4 v[44:47], v[0:1], off offset:512 nt
	global_load_dwordx4 v[40:43], v[0:1], off offset:1024 nt
	global_load_dwordx4 v[36:39], v[0:1], off offset:1536 nt
	global_load_dwordx4 v[32:35], v[0:1], off offset:2048 nt
	global_load_dwordx4 v[28:31], v[0:1], off offset:2560 nt
	global_load_dwordx4 v[24:27], v[0:1], off offset:3072 nt
	global_load_dwordx4 v[20:23], v[0:1], off offset:3584 nt
.Lrs_skip_s0:
	v_lshl_add_u64 v[90:91], s[12:13], 0, v[96:97]
	v_mov_b64_e32 v[0:1], s[0:1]
	v_mad_u64_u32 v[0:1], s[16:17], v90, s74, v[0:1]
	v_and_b32_e32 v58, 63, v84
	v_mad_i32_i24 v1, v91, s74, v1
	s_lshl_b32 s22, s26, 8
	v_lshl_add_u64 v[4:5], v[0:1], 0, s[22:23]
	v_lshlrev_b32_e32 v98, 2, v58
	v_mov_b32_e32 v99, v197
	v_lshl_add_u64 v[4:5], v[4:5], 0, v[98:99]
	global_load_dword v61, v[4:5], off offset:1024 nt
	global_load_dword v60, v[4:5], off offset:2048 nt
	global_load_dword v59, v[4:5], off offset:3072 nt
	s_movk_i32 s16, 0x1e0
	v_readfirstlane_b32 s19, v96
	s_lshl_b32 s18, s26, 7
	v_cmp_gt_i32_e64 s[42:43], s16, v84
	v_mov_b32_e32 v56, 0
	v_ashrrev_i32_e32 v101, 31, v100
	v_mov_b32_e32 v52, 0
	v_mov_b32_e32 v53, 0
	v_mov_b32_e32 v54, 0
	v_mov_b32_e32 v55, 0
	s_and_saveexec_b64 s[16:17], s[42:43]
	s_cbranch_execz .LBB0_675
	v_mad_i64_i32 v[4:5], s[28:29], s9, 15, v[100:101]
	v_lshlrev_b64 v[4:5], 11, v[4:5]
	v_lshl_add_u64 v[4:5], s[50:51], 0, v[4:5]
	s_lshl_b32 s22, s18, 2
	v_lshl_add_u64 v[4:5], v[4:5], 0, s[22:23]
	v_lshl_add_u64 v[4:5], v[4:5], 0, v[196:197]
	global_load_dwordx4 v[52:55], v[4:5], off nt

.LBB0_685:
	s_or_b64 exec, exec, s[0:1]
	s_cmp_lg_u32 s92, 2
	s_cbranch_scc1 .Lrs_nocopy
	v_mov_b32_e32 v48, v168
	v_mov_b32_e32 v49, v169
	v_mov_b32_e32 v50, v170
	v_mov_b32_e32 v51, v171
	v_mov_b32_e32 v44, v172
	v_mov_b32_e32 v45, v173
	v_mov_b32_e32 v46, v174
	v_mov_b32_e32 v47, v175
	v_mov_b32_e32 v40, v176
	v_mov_b32_e32 v41, v177
	v_mov_b32_e32 v42, v178
	v_mov_b32_e32 v43, v179
	v_mov_b32_e32 v36, v180
	v_mov_b32_e32 v37, v181
	v_mov_b32_e32 v38, v182
	v_mov_b32_e32 v39, v183
	v_mov_b32_e32 v32, v184
	v_mov_b32_e32 v33, v185
	v_mov_b32_e32 v34, v186
	v_mov_b32_e32 v35, v187
	v_mov_b32_e32 v28, v188
	v_mov_b32_e32 v29, v189
	v_mov_b32_e32 v30, v190
	v_mov_b32_e32 v31, v191
	v_mov_b32_e32 v24, v202
	v_mov_b32_e32 v25, v203
	v_mov_b32_e32 v26, v204
	v_mov_b32_e32 v27, v205
	v_mov_b32_e32 v20, v206
	v_mov_b32_e32 v21, v207
	v_mov_b32_e32 v22, v208
	v_mov_b32_e32 v23, v209
.Lrs_nocopy:
	s_cmp_lg_u32 s92, 0
	s_cbranch_scc1 .Lrs_pf_skip
	s_add_i32 s93, s8, s62
	s_cmpk_gt_i32 s93, 0x1ff
	s_cbranch_scc1 .Lrs_pf_skip
	global_load_dwordx4 v[168:171], v[210:211], off nt
	global_load_dwordx4 v[172:175], v[210:211], off offset:512 nt
	global_load_dwordx4 v[176:179], v[210:211], off offset:1024 nt
	global_load_dwordx4 v[180:183], v[210:211], off offset:1536 nt
	global_load_dwordx4 v[184:187], v[210:211], off offset:2048 nt
	global_load_dwordx4 v[188:191], v[210:211], off offset:2560 nt
	global_load_dwordx4 v[202:205], v[210:211], off offset:3072 nt
	global_load_dwordx4 v[206:209], v[210:211], off offset:3584 nt
	s_mov_b32 s92, 1
.Lrs_pf_skip:
	v_lshl_add_u32 v52, v84, 2, s79
	ds_write2st64_b32 v52, v197, v197 offset0:16 offset1:24
	v_ashrrev_i32_e32 v52, 3, v84
	v_and_b32_e32 v53, 7, v52
	v_and_b32_e32 v58, 7, v84
	v_lshlrev_b32_e32 v56, 2, v53
	v_lshlrev_b32_e32 v57, 9, v58
	v_lshlrev_b32_e32 v54, 2, v96
	v_add3_u32 v56, 0, v56, v57
	v_add3_u32 v59, 0, v54, v57
	v_add_u32_e32 v60, 0x1000, v56
	s_waitcnt lgkmcnt(0)
	s_barrier
	ds_read2_b32 v[54:55], v59 offset1:8
	ds_read2_b32 v[56:57], v60 offset1:8
	s_waitcnt lgkmcnt(0)
	v_fma_f32 v61, v54, v56, 0
	v_fmac_f32_e32 v61, v55, v57
	ds_read2_b32 v[54:55], v59 offset0:16 offset1:24
	ds_read2_b32 v[56:57], v60 offset0:16 offset1:24
	s_waitcnt lgkmcnt(0)
	v_fmac_f32_e32 v61, v54, v56
	v_fmac_f32_e32 v61, v55, v57
	ds_read2_b32 v[54:55], v59 offset0:32 offset1:40
	ds_read2_b32 v[56:57], v60 offset0:32 offset1:40
	s_waitcnt lgkmcnt(0)
	v_fmac_f32_e32 v61, v54, v56
	v_fmac_f32_e32 v61, v55, v57
	ds_read2_b32 v[54:55], v59 offset0:48 offset1:56
	ds_read2_b32 v[56:57], v60 offset0:48 offset1:56
	s_waitcnt lgkmcnt(0)
	v_fmac_f32_e32 v61, v54, v56
	v_fmac_f32_e32 v61, v55, v57
	ds_read2_b32 v[54:55], v59 offset0:64 offset1:72
	ds_read2_b32 v[56:57], v60 offset0:64 offset1:72
	s_waitcnt lgkmcnt(0)
	v_fmac_f32_e32 v61, v54, v56
	v_fmac_f32_e32 v61, v55, v57
	ds_read2_b32 v[54:55], v59 offset0:80 offset1:88
	ds_read2_b32 v[56:57], v60 offset0:80 offset1:88
	s_waitcnt lgkmcnt(0)
	v_fmac_f32_e32 v61, v54, v56
	v_fmac_f32_e32 v61, v55, v57
	ds_read2_b32 v[54:55], v59 offset0:96 offset1:104
	ds_read2_b32 v[56:57], v60 offset0:96 offset1:104
	s_waitcnt lgkmcnt(0)
	v_fmac_f32_e32 v61, v54, v56
	v_fmac_f32_e32 v61, v55, v57
	ds_read2_b32 v[54:55], v59 offset0:112 offset1:120
	ds_read2_b32 v[56:57], v60 offset0:112 offset1:120
	s_waitcnt lgkmcnt(0)
	v_fmac_f32_e32 v61, v54, v56
	v_fmac_f32_e32 v61, v55, v57
	v_and_b32_e32 v55, 64, v228
	v_xor_b32_e32 v54, 1, v228
	v_add_u32_e32 v115, 64, v55
	v_cmp_lt_i32_e32 vcc, v54, v115
	v_xor_b32_e32 v55, 2, v228
	s_nop 0
	v_cndmask_b32_e32 v54, v228, v54, vcc
	v_lshlrev_b32_e32 v114, 2, v54
	ds_bpermute_b32 v54, v114, v61
	v_cmp_lt_i32_e32 vcc, v55, v115
	s_waitcnt lgkmcnt(0)
	v_add_f32_e32 v54, v61, v54
	v_cndmask_b32_e32 v55, v228, v55, vcc
	v_lshlrev_b32_e32 v116, 2, v55
	ds_bpermute_b32 v55, v116, v54
	s_waitcnt lgkmcnt(0)
	v_add_f32_e32 v54, v54, v55
	v_xor_b32_e32 v55, 4, v228
	v_cmp_lt_i32_e32 vcc, v55, v115
	s_nop 1
	v_cndmask_b32_e32 v55, v228, v55, vcc
	v_lshlrev_b32_e32 v117, 2, v55
	ds_bpermute_b32 v55, v117, v54
	v_cmp_eq_u32_e32 vcc, 0, v58
	s_and_saveexec_b64 s[0:1], vcc
	s_cbranch_execz .LBB0_687
	s_waitcnt lgkmcnt(0)
	v_add_f32_e32 v54, v54, v55
	v_sub_u32_e32 v55, v96, v53
	v_cvt_f32_i32_e32 v55, v55
	v_cmp_ge_i32_e32 vcc, v96, v53
	v_lshl_add_u32 v52, v52, 2, 0
	v_mul_f32_e32 v55, v85, v55
	v_exp_f32_e32 v55, v55
	s_nop 0
	v_mul_f32_e32 v54, v55, v54
	v_cndmask_b32_e32 v53, 0, v54, vcc
	ds_write_b32 v52, v53 offset:16384

.LBB0_690:
	ds_read_b32 v58, v57
	s_add_i32 s12, s12, -1
	v_add_u32_e32 v57, 0xfffffe00, v57
	s_cmp_lg_u32 s12, 0
	s_waitcnt lgkmcnt(0)
	v_add_f32_e32 v56, v56, v58
	s_cbranch_scc1 .LBB0_690
	v_add3_u32 v52, s78, v53, v52
	ds_read_b32 v52, v52 offset:7680
	v_add_u32_e32 v53, v54, v53
	v_add_u32_e32 v118, 0, v196
	v_lshl_add_u32 v132, v100, 8, 0
	v_mul_f32_e32 v104, 0x41000000, v85
	s_waitcnt lgkmcnt(0)
	v_fma_f32 v52, v55, v56, -v52
	ds_write_b32 v53, v52
	ds_read_b128 v[76:79], v118 offset:12288
	ds_read_b128 v[68:71], v118 offset:12800
	ds_read_b128 v[60:63], v118 offset:13312
	ds_read_b128 v[52:55], v118 offset:13824
	ds_read_b128 v[80:83], v118 offset:14336
	ds_read_b128 v[72:75], v118 offset:14848
	ds_read_b128 v[64:67], v118 offset:15360
	ds_read_b128 v[56:59], v118 offset:15872
	ds_read_b128 v[120:123], v132
	ds_read_b128 v[124:127], v132 offset:16
	ds_read_b128 v[128:131], v132 offset:8192
	ds_read_b128 v[132:135], v132 offset:8208
	v_exp_f32_e32 v106, v104
	s_cmp_eq_u32 s92, 1
	s_cbranch_scc1 .Lrs_w_pf
	s_waitcnt vmcnt(3)
	s_branch .Lrs_w_end
.Lrs_w_pf:
	s_waitcnt vmcnt(11)
.Lrs_w_end:
	s_add_u32 s20, s20, 0xfe01000
	s_waitcnt lgkmcnt(2)
	v_pk_fma_f32 v[140:141], v[48:49], v[124:125], 0 op_sel_hi:[1,0,0]
	s_waitcnt lgkmcnt(1)
	v_pk_mul_f32 v[144:145], v[78:79], v[128:129] op_sel_hi:[1,0]
	v_pk_mul_f32 v[146:147], v[76:77], v[128:129] op_sel_hi:[1,0]
	v_pk_fma_f32 v[144:145], v[106:107], v[50:51], v[144:145] op_sel_hi:[0,1,1]
	v_pk_fma_f32 v[146:147], v[106:107], v[48:49], v[146:147] op_sel_hi:[0,1,1]
	s_waitcnt lgkmcnt(0)
	v_pk_fma_f32 v[146:147], v[80:81], v[132:133], v[146:147] op_sel_hi:[1,0,1]
	v_pk_fma_f32 v[144:145], v[82:83], v[132:133], v[144:145] op_sel_hi:[1,0,1]
	v_pk_fma_f32 v[136:137], v[48:49], v[120:121], 0 op_sel_hi:[1,0,0]
	v_pk_fma_f32 v[138:139], v[50:51], v[120:121], 0 op_sel_hi:[1,0,0]
	v_pk_fma_f32 v[142:143], v[50:51], v[124:125], 0 op_sel_hi:[1,0,0]
	v_pk_fma_f32 v[148:149], v[48:49], v[120:121], 0 op_sel:[0,1,0] op_sel_hi:[1,1,0]
	v_pk_fma_f32 v[150:151], v[50:51], v[120:121], 0 op_sel:[0,1,0] op_sel_hi:[1,1,0]
	v_pk_fma_f32 v[152:153], v[48:49], v[124:125], 0 op_sel:[0,1,0] op_sel_hi:[1,1,0]
	v_pk_fma_f32 v[154:155], v[50:51], v[124:125], 0 op_sel:[0,1,0] op_sel_hi:[1,1,0]
	v_pk_fma_f32 v[120:121], v[70:71], v[128:129], v[144:145] op_sel:[0,1,0]
	v_pk_fma_f32 v[124:125], v[68:69], v[128:129], v[146:147] op_sel:[0,1,0]
	s_addc_u32 s21, s21, 0
	s_lshl_b64 s[0:1], s[0:1], 2
	v_pk_fma_f32 v[124:125], v[72:73], v[132:133], v[124:125] op_sel:[0,1,0]
	v_pk_fma_f32 v[120:121], v[74:75], v[132:133], v[120:121] op_sel:[0,1,0]
	v_pk_fma_f32 v[132:133], v[48:49], v[122:123], 0 op_sel_hi:[1,0,0]
	v_pk_fma_f32 v[144:145], v[50:51], v[122:123], 0 op_sel_hi:[1,0,0]
	v_mov_b32_e32 v122, v123
	s_add_u32 s0, s3, s0
	v_pk_fma_f32 v[120:121], v[62:63], v[130:131], v[120:121] op_sel_hi:[1,0,1]
	v_pk_fma_f32 v[124:125], v[60:61], v[130:131], v[124:125] op_sel_hi:[1,0,1]
	v_pk_fma_f32 v[158:159], v[48:49], v[122:123], 0 op_sel_hi:[1,0,0]
	v_pk_fma_f32 v[160:161], v[50:51], v[122:123], 0 op_sel_hi:[1,0,0]
	v_mov_b32_e32 v122, v127
	s_addc_u32 s1, s4, s1
	v_lshlrev_b32_e32 v119, 3, v100
	v_pk_fma_f32 v[146:147], v[48:49], v[126:127], 0 op_sel_hi:[1,0,0]
	v_pk_fma_f32 v[124:125], v[64:65], v[134:135], v[124:125] op_sel_hi:[1,0,1]
	v_pk_fma_f32 v[120:121], v[66:67], v[134:135], v[120:121] op_sel_hi:[1,0,1]
	v_pk_fma_f32 v[162:163], v[48:49], v[122:123], 0 op_sel_hi:[1,0,0]
	v_mov_b32_e32 v48, v131
	v_lshl_add_u64 v[104:105], s[0:1], 0, v[196:197]
	v_pk_fma_f32 v[156:157], v[50:51], v[126:127], 0 op_sel_hi:[1,0,0]
	v_pk_fma_f32 v[164:165], v[50:51], v[122:123], 0 op_sel_hi:[1,0,0]
	v_pk_fma_f32 v[50:51], v[54:55], v[48:49], v[120:121] op_sel_hi:[1,0,1]
	v_pk_fma_f32 v[48:49], v[52:53], v[48:49], v[124:125] op_sel_hi:[1,0,1]
	v_mov_b32_e32 v120, v135
	v_or_b32_e32 v166, 1, v119
	v_pk_fma_f32 v[48:49], v[56:57], v[120:121], v[48:49] op_sel_hi:[1,0,1]
	v_pk_fma_f32 v[50:51], v[58:59], v[120:121], v[50:51] op_sel_hi:[1,0,1]
	v_lshl_add_u64 v[102:103], v[102:103], 2, v[104:105]
	v_lshl_add_u32 v128, v166, 5, 0
	ds_read_b128 v[120:123], v128
	global_store_dwordx4 v[102:103], v[48:51], off nt
	ds_read_b128 v[48:51], v128 offset:16
	ds_read_b128 v[124:127], v128 offset:8192
	ds_read_b128 v[128:131], v128 offset:8208
	s_waitcnt lgkmcnt(3)
	v_pk_fma_f32 v[102:103], v[46:47], v[120:121], v[138:139] op_sel_hi:[1,0,1]
	v_pk_fma_f32 v[134:135], v[44:45], v[120:121], v[136:137] op_sel_hi:[1,0,1]
	s_waitcnt lgkmcnt(2)
	v_pk_fma_f32 v[136:137], v[46:47], v[48:49], v[142:143] op_sel_hi:[1,0,1]
	v_pk_fma_f32 v[138:139], v[44:45], v[48:49], v[140:141] op_sel_hi:[1,0,1]
	s_waitcnt lgkmcnt(1)
	v_pk_mul_f32 v[140:141], v[78:79], v[124:125] op_sel_hi:[1,0]
	v_pk_mul_f32 v[142:143], v[76:77], v[124:125] op_sel_hi:[1,0]
	v_pk_fma_f32 v[140:141], v[106:107], v[46:47], v[140:141] op_sel_hi:[0,1,1]
	v_pk_fma_f32 v[142:143], v[106:107], v[44:45], v[142:143] op_sel_hi:[0,1,1]
	s_waitcnt lgkmcnt(0)
	v_pk_fma_f32 v[140:141], v[82:83], v[128:129], v[140:141] op_sel_hi:[1,0,1]
	v_pk_fma_f32 v[142:143], v[80:81], v[128:129], v[142:143] op_sel_hi:[1,0,1]
	v_pk_fma_f32 v[150:151], v[46:47], v[120:121], v[150:151] op_sel:[0,1,0]
	v_pk_fma_f32 v[148:149], v[44:45], v[120:121], v[148:149] op_sel:[0,1,0]
	v_pk_fma_f32 v[154:155], v[46:47], v[48:49], v[154:155] op_sel:[0,1,0]
	v_pk_fma_f32 v[152:153], v[44:45], v[48:49], v[152:153] op_sel:[0,1,0]
	v_pk_fma_f32 v[48:49], v[70:71], v[124:125], v[140:141] op_sel:[0,1,0]
	v_pk_fma_f32 v[120:121], v[68:69], v[124:125], v[142:143] op_sel:[0,1,0]
	v_pk_fma_f32 v[48:49], v[74:75], v[128:129], v[48:49] op_sel:[0,1,0]
	v_pk_fma_f32 v[120:121], v[72:73], v[128:129], v[120:121] op_sel:[0,1,0]
	v_pk_fma_f32 v[140:141], v[46:47], v[50:51], v[156:157] op_sel_hi:[1,0,1]
	v_pk_fma_f32 v[142:143], v[44:45], v[50:51], v[146:147] op_sel_hi:[1,0,1]
	v_mov_b32_e32 v50, v123
	v_pk_fma_f32 v[128:129], v[46:47], v[122:123], v[144:145] op_sel_hi:[1,0,1]
	v_pk_fma_f32 v[48:49], v[62:63], v[126:127], v[48:49] op_sel_hi:[1,0,1]
	v_pk_fma_f32 v[120:121], v[60:61], v[126:127], v[120:121] op_sel_hi:[1,0,1]
	v_pk_fma_f32 v[144:145], v[46:47], v[50:51], v[160:161] op_sel_hi:[1,0,1]
	v_pk_fma_f32 v[146:147], v[44:45], v[50:51], v[158:159] op_sel_hi:[1,0,1]
	v_mov_b32_e32 v50, v51
	v_pk_fma_f32 v[132:133], v[44:45], v[122:123], v[132:133] op_sel_hi:[1,0,1]
	v_pk_fma_f32 v[48:49], v[66:67], v[130:131], v[48:49] op_sel_hi:[1,0,1]
	v_pk_fma_f32 v[120:121], v[64:65], v[130:131], v[120:121] op_sel_hi:[1,0,1]
	v_pk_fma_f32 v[158:159], v[44:45], v[50:51], v[162:163] op_sel_hi:[1,0,1]
	v_mov_b32_e32 v44, v127
	v_pk_fma_f32 v[156:157], v[46:47], v[50:51], v[164:165] op_sel_hi:[1,0,1]
	v_pk_fma_f32 v[46:47], v[54:55], v[44:45], v[48:49] op_sel_hi:[1,0,1]
	v_pk_fma_f32 v[44:45], v[52:53], v[44:45], v[120:121] op_sel_hi:[1,0,1]
	v_mov_b32_e32 v48, v131
	v_pk_fma_f32 v[46:47], v[58:59], v[48:49], v[46:47] op_sel_hi:[1,0,1]
	v_pk_fma_f32 v[44:45], v[56:57], v[48:49], v[44:45] op_sel_hi:[1,0,1]
	v_lshlrev_b32_e32 v48, 7, v166
	v_ashrrev_i32_e32 v49, 31, v48
	v_or_b32_e32 v162, 2, v119
	v_lshl_add_u64 v[120:121], v[48:49], 2, v[104:105]
	v_lshl_add_u32 v124, v162, 5, 0
	ds_read_b128 v[48:51], v124
	global_store_dwordx4 v[120:121], v[44:47], off nt
	ds_read_b128 v[44:47], v124 offset:16
	ds_read_b128 v[120:123], v124 offset:8192
	ds_read_b128 v[124:127], v124 offset:8208
	s_waitcnt lgkmcnt(3)
	v_pk_fma_f32 v[130:131], v[40:41], v[48:49], v[134:135] op_sel_hi:[1,0,1]
	s_waitcnt lgkmcnt(2)
	v_pk_fma_f32 v[134:135], v[40:41], v[44:45], v[138:139] op_sel_hi:[1,0,1]
	s_waitcnt lgkmcnt(1)
	v_pk_mul_f32 v[138:139], v[78:79], v[120:121] op_sel_hi:[1,0]
	v_pk_mul_f32 v[160:161], v[76:77], v[120:121] op_sel_hi:[1,0]
	v_pk_fma_f32 v[138:139], v[106:107], v[42:43], v[138:139] op_sel_hi:[0,1,1]
	v_pk_fma_f32 v[160:161], v[106:107], v[40:41], v[160:161] op_sel_hi:[0,1,1]
	s_waitcnt lgkmcnt(0)
	v_pk_fma_f32 v[138:139], v[82:83], v[124:125], v[138:139] op_sel_hi:[1,0,1]
	v_pk_fma_f32 v[160:161], v[80:81], v[124:125], v[160:161] op_sel_hi:[1,0,1]
	v_pk_fma_f32 v[102:103], v[42:43], v[48:49], v[102:103] op_sel_hi:[1,0,1]
	v_pk_fma_f32 v[136:137], v[42:43], v[44:45], v[136:137] op_sel_hi:[1,0,1]
	v_pk_fma_f32 v[148:149], v[40:41], v[48:49], v[148:149] op_sel:[0,1,0]
	v_pk_fma_f32 v[150:151], v[42:43], v[48:49], v[150:151] op_sel:[0,1,0]
	v_pk_fma_f32 v[152:153], v[40:41], v[44:45], v[152:153] op_sel:[0,1,0]
	v_pk_fma_f32 v[154:155], v[42:43], v[44:45], v[154:155] op_sel:[0,1,0]
	v_pk_fma_f32 v[44:45], v[70:71], v[120:121], v[138:139] op_sel:[0,1,0]
	v_pk_fma_f32 v[48:49], v[68:69], v[120:121], v[160:161] op_sel:[0,1,0]
	v_pk_fma_f32 v[44:45], v[74:75], v[124:125], v[44:45] op_sel:[0,1,0]
	v_pk_fma_f32 v[48:49], v[72:73], v[124:125], v[48:49] op_sel:[0,1,0]
	v_pk_fma_f32 v[124:125], v[40:41], v[50:51], v[132:133] op_sel_hi:[1,0,1]
	v_pk_fma_f32 v[132:133], v[40:41], v[46:47], v[142:143] op_sel_hi:[1,0,1]
	v_pk_fma_f32 v[138:139], v[42:43], v[46:47], v[140:141] op_sel_hi:[1,0,1]
	v_mov_b32_e32 v46, v51
	v_pk_fma_f32 v[44:45], v[62:63], v[122:123], v[44:45] op_sel_hi:[1,0,1]
	v_pk_fma_f32 v[48:49], v[60:61], v[122:123], v[48:49] op_sel_hi:[1,0,1]
	v_pk_fma_f32 v[140:141], v[40:41], v[46:47], v[146:147] op_sel_hi:[1,0,1]
	v_pk_fma_f32 v[142:143], v[42:43], v[46:47], v[144:145] op_sel_hi:[1,0,1]
	v_mov_b32_e32 v46, v47
	v_pk_fma_f32 v[44:45], v[66:67], v[126:127], v[44:45] op_sel_hi:[1,0,1]
	v_pk_fma_f32 v[48:49], v[64:65], v[126:127], v[48:49] op_sel_hi:[1,0,1]
	v_pk_fma_f32 v[144:145], v[40:41], v[46:47], v[158:159] op_sel_hi:[1,0,1]
	v_mov_b32_e32 v40, v123
	v_pk_fma_f32 v[128:129], v[42:43], v[50:51], v[128:129] op_sel_hi:[1,0,1]
	v_pk_fma_f32 v[146:147], v[42:43], v[46:47], v[156:157] op_sel_hi:[1,0,1]
	v_pk_fma_f32 v[42:43], v[54:55], v[40:41], v[44:45] op_sel_hi:[1,0,1]
	v_pk_fma_f32 v[40:41], v[52:53], v[40:41], v[48:49] op_sel_hi:[1,0,1]
	v_mov_b32_e32 v44, v127
	v_pk_fma_f32 v[42:43], v[58:59], v[44:45], v[42:43] op_sel_hi:[1,0,1]
	v_pk_fma_f32 v[40:41], v[56:57], v[44:45], v[40:41] op_sel_hi:[1,0,1]
	v_lshlrev_b32_e32 v44, 7, v162
	v_ashrrev_i32_e32 v45, 31, v44
	v_or_b32_e32 v158, 3, v119
	v_lshl_add_u64 v[48:49], v[44:45], 2, v[104:105]
	v_lshl_add_u32 v120, v158, 5, 0
	ds_read_b128 v[44:47], v120
	global_store_dwordx4 v[48:49], v[40:43], off nt
	ds_read_b128 v[40:43], v120 offset:16
	ds_read_b128 v[48:51], v120 offset:8192
	ds_read_b128 v[120:123], v120 offset:8208
	s_waitcnt lgkmcnt(3)
	v_pk_fma_f32 v[126:127], v[36:37], v[44:45], v[130:131] op_sel_hi:[1,0,1]
	s_waitcnt lgkmcnt(2)
	v_pk_fma_f32 v[130:131], v[38:39], v[40:41], v[136:137] op_sel_hi:[1,0,1]
	s_waitcnt lgkmcnt(1)
	v_pk_mul_f32 v[136:137], v[78:79], v[48:49] op_sel_hi:[1,0]
	v_pk_mul_f32 v[156:157], v[76:77], v[48:49] op_sel_hi:[1,0]
	v_pk_fma_f32 v[136:137], v[106:107], v[38:39], v[136:137] op_sel_hi:[0,1,1]
	v_pk_fma_f32 v[156:157], v[106:107], v[36:37], v[156:157] op_sel_hi:[0,1,1]
	s_waitcnt lgkmcnt(0)
	v_pk_fma_f32 v[136:137], v[82:83], v[120:121], v[136:137] op_sel_hi:[1,0,1]
	v_pk_fma_f32 v[156:157], v[80:81], v[120:121], v[156:157] op_sel_hi:[1,0,1]
	v_pk_fma_f32 v[102:103], v[38:39], v[44:45], v[102:103] op_sel_hi:[1,0,1]
	v_pk_fma_f32 v[134:135], v[36:37], v[40:41], v[134:135] op_sel_hi:[1,0,1]
	v_pk_fma_f32 v[150:151], v[38:39], v[44:45], v[150:151] op_sel:[0,1,0]
	v_pk_fma_f32 v[148:149], v[36:37], v[44:45], v[148:149] op_sel:[0,1,0]
	v_pk_fma_f32 v[154:155], v[38:39], v[40:41], v[154:155] op_sel:[0,1,0]
	v_pk_fma_f32 v[152:153], v[36:37], v[40:41], v[152:153] op_sel:[0,1,0]
	v_pk_fma_f32 v[40:41], v[70:71], v[48:49], v[136:137] op_sel:[0,1,0]
	v_pk_fma_f32 v[44:45], v[68:69], v[48:49], v[156:157] op_sel:[0,1,0]
	v_pk_fma_f32 v[40:41], v[74:75], v[120:121], v[40:41] op_sel:[0,1,0]
	v_pk_fma_f32 v[44:45], v[72:73], v[120:121], v[44:45] op_sel:[0,1,0]
	v_pk_fma_f32 v[120:121], v[38:39], v[46:47], v[128:129] op_sel_hi:[1,0,1]
	v_pk_fma_f32 v[128:129], v[38:39], v[42:43], v[138:139] op_sel_hi:[1,0,1]
	v_pk_fma_f32 v[132:133], v[36:37], v[42:43], v[132:133] op_sel_hi:[1,0,1]
	v_mov_b32_e32 v42, v47
	v_pk_fma_f32 v[40:41], v[62:63], v[50:51], v[40:41] op_sel_hi:[1,0,1]
	v_pk_fma_f32 v[44:45], v[60:61], v[50:51], v[44:45] op_sel_hi:[1,0,1]
	v_pk_fma_f32 v[136:137], v[38:39], v[42:43], v[142:143] op_sel_hi:[1,0,1]
	v_pk_fma_f32 v[138:139], v[36:37], v[42:43], v[140:141] op_sel_hi:[1,0,1]
	v_mov_b32_e32 v42, v43
	v_pk_fma_f32 v[124:125], v[36:37], v[46:47], v[124:125] op_sel_hi:[1,0,1]
	v_pk_fma_f32 v[40:41], v[66:67], v[122:123], v[40:41] op_sel_hi:[1,0,1]
	v_pk_fma_f32 v[44:45], v[64:65], v[122:123], v[44:45] op_sel_hi:[1,0,1]
	v_pk_fma_f32 v[142:143], v[36:37], v[42:43], v[144:145] op_sel_hi:[1,0,1]
	v_mov_b32_e32 v36, v51
	v_pk_fma_f32 v[140:141], v[38:39], v[42:43], v[146:147] op_sel_hi:[1,0,1]
	v_pk_fma_f32 v[38:39], v[54:55], v[36:37], v[40:41] op_sel_hi:[1,0,1]
	v_pk_fma_f32 v[36:37], v[52:53], v[36:37], v[44:45] op_sel_hi:[1,0,1]
	v_mov_b32_e32 v40, v123
	v_pk_fma_f32 v[38:39], v[58:59], v[40:41], v[38:39] op_sel_hi:[1,0,1]
	v_pk_fma_f32 v[36:37], v[56:57], v[40:41], v[36:37] op_sel_hi:[1,0,1]
	v_lshlrev_b32_e32 v40, 7, v158
	v_ashrrev_i32_e32 v41, 31, v40
	v_or_b32_e32 v156, 4, v119
	v_lshl_add_u64 v[44:45], v[40:41], 2, v[104:105]
	v_lshl_add_u32 v48, v156, 5, 0
	ds_read_b128 v[40:43], v48
	global_store_dwordx4 v[44:45], v[36:39], off nt
	ds_read_b128 v[36:39], v48 offset:16
	ds_read_b128 v[44:47], v48 offset:8192
	ds_read_b128 v[48:51], v48 offset:8208
	s_waitcnt lgkmcnt(3)
	v_pk_fma_f32 v[122:123], v[32:33], v[40:41], v[126:127] op_sel_hi:[1,0,1]
	s_waitcnt lgkmcnt(2)
	v_pk_fma_f32 v[126:127], v[32:33], v[36:37], v[134:135] op_sel_hi:[1,0,1]
	s_waitcnt lgkmcnt(1)
	v_pk_mul_f32 v[134:135], v[78:79], v[44:45] op_sel_hi:[1,0]
	v_pk_mul_f32 v[144:145], v[76:77], v[44:45] op_sel_hi:[1,0]
	v_pk_fma_f32 v[134:135], v[106:107], v[34:35], v[134:135] op_sel_hi:[0,1,1]
	v_pk_fma_f32 v[144:145], v[106:107], v[32:33], v[144:145] op_sel_hi:[0,1,1]
	s_waitcnt lgkmcnt(0)
	v_pk_fma_f32 v[134:135], v[82:83], v[48:49], v[134:135] op_sel_hi:[1,0,1]
	v_pk_fma_f32 v[144:145], v[80:81], v[48:49], v[144:145] op_sel_hi:[1,0,1]
	v_pk_fma_f32 v[102:103], v[34:35], v[40:41], v[102:103] op_sel_hi:[1,0,1]
	v_pk_fma_f32 v[130:131], v[34:35], v[36:37], v[130:131] op_sel_hi:[1,0,1]
	v_pk_fma_f32 v[146:147], v[32:33], v[40:41], v[148:149] op_sel:[0,1,0]
	v_pk_fma_f32 v[148:149], v[34:35], v[40:41], v[150:151] op_sel:[0,1,0]
	v_pk_fma_f32 v[150:151], v[32:33], v[36:37], v[152:153] op_sel:[0,1,0]
	v_pk_fma_f32 v[152:153], v[34:35], v[36:37], v[154:155] op_sel:[0,1,0]
	v_pk_fma_f32 v[36:37], v[70:71], v[44:45], v[134:135] op_sel:[0,1,0]
	v_pk_fma_f32 v[40:41], v[68:69], v[44:45], v[144:145] op_sel:[0,1,0]
	v_pk_fma_f32 v[36:37], v[74:75], v[48:49], v[36:37] op_sel:[0,1,0]
	v_pk_fma_f32 v[40:41], v[72:73], v[48:49], v[40:41] op_sel:[0,1,0]
	v_pk_fma_f32 v[48:49], v[32:33], v[42:43], v[124:125] op_sel_hi:[1,0,1]
	v_pk_fma_f32 v[124:125], v[32:33], v[38:39], v[132:133] op_sel_hi:[1,0,1]
	v_pk_fma_f32 v[128:129], v[34:35], v[38:39], v[128:129] op_sel_hi:[1,0,1]
	v_mov_b32_e32 v38, v43
	v_pk_fma_f32 v[36:37], v[62:63], v[46:47], v[36:37] op_sel_hi:[1,0,1]
	v_pk_fma_f32 v[40:41], v[60:61], v[46:47], v[40:41] op_sel_hi:[1,0,1]
	v_pk_fma_f32 v[132:133], v[32:33], v[38:39], v[138:139] op_sel_hi:[1,0,1]
	v_pk_fma_f32 v[134:135], v[34:35], v[38:39], v[136:137] op_sel_hi:[1,0,1]
	v_mov_b32_e32 v38, v39
	v_pk_fma_f32 v[36:37], v[66:67], v[50:51], v[36:37] op_sel_hi:[1,0,1]
	v_pk_fma_f32 v[40:41], v[64:65], v[50:51], v[40:41] op_sel_hi:[1,0,1]
	v_pk_fma_f32 v[136:137], v[32:33], v[38:39], v[142:143] op_sel_hi:[1,0,1]
	v_mov_b32_e32 v32, v47
	v_pk_fma_f32 v[120:121], v[34:35], v[42:43], v[120:121] op_sel_hi:[1,0,1]
	v_pk_fma_f32 v[138:139], v[34:35], v[38:39], v[140:141] op_sel_hi:[1,0,1]
	v_pk_fma_f32 v[34:35], v[54:55], v[32:33], v[36:37] op_sel_hi:[1,0,1]
	v_pk_fma_f32 v[32:33], v[52:53], v[32:33], v[40:41] op_sel_hi:[1,0,1]
	v_mov_b32_e32 v36, v51
	v_pk_fma_f32 v[34:35], v[58:59], v[36:37], v[34:35] op_sel_hi:[1,0,1]
	v_pk_fma_f32 v[32:33], v[56:57], v[36:37], v[32:33] op_sel_hi:[1,0,1]
	v_lshlrev_b32_e32 v36, 7, v156
	v_ashrrev_i32_e32 v37, 31, v36
	v_or_b32_e32 v154, 5, v119
	v_lshl_add_u64 v[40:41], v[36:37], 2, v[104:105]
	v_lshl_add_u32 v44, v154, 5, 0
	ds_read_b128 v[36:39], v44
	global_store_dwordx4 v[40:41], v[32:35], off nt
	ds_read_b128 v[32:35], v44 offset:16
	ds_read_b128 v[40:43], v44 offset:8192
	ds_read_b128 v[44:47], v44 offset:8208
	s_waitcnt lgkmcnt(3)
	v_pk_fma_f32 v[50:51], v[30:31], v[36:37], v[102:103] op_sel_hi:[1,0,1]
	v_pk_fma_f32 v[102:103], v[28:29], v[36:37], v[122:123] op_sel_hi:[1,0,1]
	s_waitcnt lgkmcnt(2)
	v_pk_fma_f32 v[122:123], v[30:31], v[32:33], v[130:131] op_sel_hi:[1,0,1]
	s_waitcnt lgkmcnt(1)
	v_pk_mul_f32 v[130:131], v[78:79], v[40:41] op_sel_hi:[1,0]
	v_pk_mul_f32 v[140:141], v[76:77], v[40:41] op_sel_hi:[1,0]
	v_pk_fma_f32 v[130:131], v[106:107], v[30:31], v[130:131] op_sel_hi:[0,1,1]
	v_pk_fma_f32 v[140:141], v[106:107], v[28:29], v[140:141] op_sel_hi:[0,1,1]
	s_waitcnt lgkmcnt(0)
	v_pk_fma_f32 v[130:131], v[82:83], v[44:45], v[130:131] op_sel_hi:[1,0,1]
	v_pk_fma_f32 v[140:141], v[80:81], v[44:45], v[140:141] op_sel_hi:[1,0,1]
	v_pk_fma_f32 v[126:127], v[28:29], v[32:33], v[126:127] op_sel_hi:[1,0,1]
	v_pk_fma_f32 v[142:143], v[30:31], v[36:37], v[148:149] op_sel:[0,1,0]
	v_pk_fma_f32 v[144:145], v[28:29], v[36:37], v[146:147] op_sel:[0,1,0]
	v_pk_fma_f32 v[146:147], v[30:31], v[32:33], v[152:153] op_sel:[0,1,0]
	v_pk_fma_f32 v[148:149], v[28:29], v[32:33], v[150:151] op_sel:[0,1,0]
	v_pk_fma_f32 v[32:33], v[70:71], v[40:41], v[130:131] op_sel:[0,1,0]
	v_pk_fma_f32 v[36:37], v[68:69], v[40:41], v[140:141] op_sel:[0,1,0]
	v_pk_fma_f32 v[32:33], v[74:75], v[44:45], v[32:33] op_sel:[0,1,0]
	v_pk_fma_f32 v[36:37], v[72:73], v[44:45], v[36:37] op_sel:[0,1,0]
	v_pk_fma_f32 v[44:45], v[30:31], v[38:39], v[120:121] op_sel_hi:[1,0,1]
	v_pk_fma_f32 v[120:121], v[30:31], v[34:35], v[128:129] op_sel_hi:[1,0,1]
	v_pk_fma_f32 v[124:125], v[28:29], v[34:35], v[124:125] op_sel_hi:[1,0,1]
	v_mov_b32_e32 v34, v39
	v_pk_fma_f32 v[32:33], v[62:63], v[42:43], v[32:33] op_sel_hi:[1,0,1]
	v_pk_fma_f32 v[36:37], v[60:61], v[42:43], v[36:37] op_sel_hi:[1,0,1]
	v_pk_fma_f32 v[128:129], v[30:31], v[34:35], v[134:135] op_sel_hi:[1,0,1]
	v_pk_fma_f32 v[130:131], v[28:29], v[34:35], v[132:133] op_sel_hi:[1,0,1]
	v_mov_b32_e32 v34, v35
	v_pk_fma_f32 v[48:49], v[28:29], v[38:39], v[48:49] op_sel_hi:[1,0,1]
	v_pk_fma_f32 v[32:33], v[66:67], v[46:47], v[32:33] op_sel_hi:[1,0,1]
	v_pk_fma_f32 v[36:37], v[64:65], v[46:47], v[36:37] op_sel_hi:[1,0,1]
	v_pk_fma_f32 v[134:135], v[28:29], v[34:35], v[136:137] op_sel_hi:[1,0,1]
	v_mov_b32_e32 v28, v43
	v_pk_fma_f32 v[132:133], v[30:31], v[34:35], v[138:139] op_sel_hi:[1,0,1]
	v_pk_fma_f32 v[30:31], v[54:55], v[28:29], v[32:33] op_sel_hi:[1,0,1]
	v_pk_fma_f32 v[28:29], v[52:53], v[28:29], v[36:37] op_sel_hi:[1,0,1]
	v_mov_b32_e32 v32, v47
	v_pk_fma_f32 v[30:31], v[58:59], v[32:33], v[30:31] op_sel_hi:[1,0,1]
	v_pk_fma_f32 v[28:29], v[56:57], v[32:33], v[28:29] op_sel_hi:[1,0,1]
	v_lshlrev_b32_e32 v32, 7, v154
	v_ashrrev_i32_e32 v33, 31, v32
	v_or_b32_e32 v150, 6, v119
	v_lshl_add_u64 v[36:37], v[32:33], 2, v[104:105]
	v_lshl_add_u32 v40, v150, 5, 0
	ds_read_b128 v[32:35], v40
	global_store_dwordx4 v[36:37], v[28:31], off nt
	ds_read_b128 v[28:31], v40 offset:16
	ds_read_b128 v[36:39], v40 offset:8192
	ds_read_b128 v[40:43], v40 offset:8208
	v_or_b32_e32 v119, 7, v119
	s_waitcnt lgkmcnt(3)
	v_pk_fma_f32 v[46:47], v[24:25], v[32:33], v[102:103] op_sel_hi:[1,0,1]
	s_waitcnt lgkmcnt(2)
	v_pk_fma_f32 v[102:103], v[24:25], v[28:29], v[126:127] op_sel_hi:[1,0,1]
	s_waitcnt lgkmcnt(1)
	v_pk_mul_f32 v[126:127], v[78:79], v[36:37] op_sel_hi:[1,0]
	v_pk_mul_f32 v[136:137], v[76:77], v[36:37] op_sel_hi:[1,0]
	v_pk_fma_f32 v[126:127], v[106:107], v[26:27], v[126:127] op_sel_hi:[0,1,1]
	v_pk_fma_f32 v[136:137], v[106:107], v[24:25], v[136:137] op_sel_hi:[0,1,1]
	s_waitcnt lgkmcnt(0)
	v_pk_fma_f32 v[126:127], v[82:83], v[40:41], v[126:127] op_sel_hi:[1,0,1]
	v_pk_fma_f32 v[136:137], v[80:81], v[40:41], v[136:137] op_sel_hi:[1,0,1]
	v_pk_fma_f32 v[50:51], v[26:27], v[32:33], v[50:51] op_sel_hi:[1,0,1]
	v_pk_fma_f32 v[122:123], v[26:27], v[28:29], v[122:123] op_sel_hi:[1,0,1]
	v_pk_fma_f32 v[138:139], v[24:25], v[32:33], v[144:145] op_sel:[0,1,0]
	v_pk_fma_f32 v[140:141], v[26:27], v[32:33], v[142:143] op_sel:[0,1,0]
	v_pk_fma_f32 v[142:143], v[24:25], v[28:29], v[148:149] op_sel:[0,1,0]
	v_pk_fma_f32 v[144:145], v[26:27], v[28:29], v[146:147] op_sel:[0,1,0]
	v_pk_fma_f32 v[28:29], v[70:71], v[36:37], v[126:127] op_sel:[0,1,0]
	v_pk_fma_f32 v[32:33], v[68:69], v[36:37], v[136:137] op_sel:[0,1,0]
	v_pk_fma_f32 v[28:29], v[74:75], v[40:41], v[28:29] op_sel:[0,1,0]
	v_pk_fma_f32 v[32:33], v[72:73], v[40:41], v[32:33] op_sel:[0,1,0]
	v_pk_fma_f32 v[124:125], v[24:25], v[30:31], v[124:125] op_sel_hi:[1,0,1]
	v_pk_fma_f32 v[120:121], v[26:27], v[30:31], v[120:121] op_sel_hi:[1,0,1]
	v_mov_b32_e32 v30, v35
	v_pk_fma_f32 v[28:29], v[62:63], v[38:39], v[28:29] op_sel_hi:[1,0,1]
	v_pk_fma_f32 v[32:33], v[60:61], v[38:39], v[32:33] op_sel_hi:[1,0,1]
	v_pk_fma_f32 v[130:131], v[24:25], v[30:31], v[130:131] op_sel_hi:[1,0,1]
	v_pk_fma_f32 v[128:129], v[26:27], v[30:31], v[128:129] op_sel_hi:[1,0,1]
	v_mov_b32_e32 v30, v31
	v_pk_fma_f32 v[126:127], v[24:25], v[34:35], v[48:49] op_sel_hi:[1,0,1]
	v_pk_fma_f32 v[28:29], v[66:67], v[42:43], v[28:29] op_sel_hi:[1,0,1]
	v_pk_fma_f32 v[32:33], v[64:65], v[42:43], v[32:33] op_sel_hi:[1,0,1]
	v_pk_fma_f32 v[134:135], v[24:25], v[30:31], v[134:135] op_sel_hi:[1,0,1]
	v_mov_b32_e32 v24, v39
	v_pk_fma_f32 v[136:137], v[26:27], v[34:35], v[44:45] op_sel_hi:[1,0,1]
	v_pk_fma_f32 v[132:133], v[26:27], v[30:31], v[132:133] op_sel_hi:[1,0,1]
	v_pk_fma_f32 v[26:27], v[54:55], v[24:25], v[28:29] op_sel_hi:[1,0,1]
	v_pk_fma_f32 v[24:25], v[52:53], v[24:25], v[32:33] op_sel_hi:[1,0,1]
	v_mov_b32_e32 v28, v43
	v_pk_fma_f32 v[26:27], v[58:59], v[28:29], v[26:27] op_sel_hi:[1,0,1]
	v_pk_fma_f32 v[24:25], v[56:57], v[28:29], v[24:25] op_sel_hi:[1,0,1]
	v_lshlrev_b32_e32 v28, 7, v150
	v_ashrrev_i32_e32 v29, 31, v28
	v_lshl_add_u64 v[32:33], v[28:29], 2, v[104:105]
	v_lshl_add_u32 v36, v119, 5, 0
	ds_read_b128 v[28:31], v36
	global_store_dwordx4 v[32:33], v[24:27], off nt
	ds_read_b128 v[24:27], v36 offset:16
	ds_read_b128 v[32:35], v36 offset:8192
	ds_read_b128 v[36:39], v36 offset:8208
	s_waitcnt lgkmcnt(3)
	v_pk_fma_f32 v[42:43], v[22:23], v[28:29], v[50:51] op_sel_hi:[1,0,1]
	s_waitcnt lgkmcnt(1)
	v_pk_mul_f32 v[50:51], v[76:77], v[32:33] op_sel_hi:[1,0]
	v_pk_mul_f32 v[48:49], v[78:79], v[32:33] op_sel_hi:[1,0]
	v_pk_fma_f32 v[50:51], v[106:107], v[20:21], v[50:51] op_sel_hi:[0,1,1]
	v_pk_fma_f32 v[48:49], v[106:107], v[22:23], v[48:49] op_sel_hi:[0,1,1]
	s_waitcnt lgkmcnt(0)
	v_pk_fma_f32 v[80:81], v[80:81], v[36:37], v[50:51] op_sel_hi:[1,0,1]
	v_pk_fma_f32 v[40:41], v[20:21], v[28:29], v[46:47] op_sel_hi:[1,0,1]
	v_pk_fma_f32 v[82:83], v[82:83], v[36:37], v[48:49] op_sel_hi:[1,0,1]
	v_pk_fma_f32 v[50:51], v[22:23], v[28:29], v[140:141] op_sel:[0,1,0]
	v_pk_fma_f32 v[48:49], v[20:21], v[28:29], v[138:139] op_sel:[0,1,0]
	v_pk_fma_f32 v[28:29], v[68:69], v[32:33], v[80:81] op_sel:[0,1,0]
	v_pk_fma_f32 v[46:47], v[22:23], v[24:25], v[122:123] op_sel_hi:[1,0,1]
	v_pk_fma_f32 v[44:45], v[20:21], v[24:25], v[102:103] op_sel_hi:[1,0,1]
	v_pk_fma_f32 v[78:79], v[22:23], v[24:25], v[144:145] op_sel:[0,1,0]
	v_pk_fma_f32 v[76:77], v[20:21], v[24:25], v[142:143] op_sel:[0,1,0]
	v_pk_fma_f32 v[24:25], v[70:71], v[32:33], v[82:83] op_sel:[0,1,0]
	v_pk_fma_f32 v[28:29], v[72:73], v[36:37], v[28:29] op_sel:[0,1,0]
	v_pk_fma_f32 v[24:25], v[74:75], v[36:37], v[24:25] op_sel:[0,1,0]
	v_pk_fma_f32 v[74:75], v[22:23], v[26:27], v[120:121] op_sel_hi:[1,0,1]
	v_pk_fma_f32 v[72:73], v[20:21], v[26:27], v[124:125] op_sel_hi:[1,0,1]
	v_pk_fma_f32 v[28:29], v[60:61], v[34:35], v[28:29] op_sel_hi:[1,0,1]
	v_mov_b32_e32 v26, v31
	v_pk_fma_f32 v[70:71], v[22:23], v[30:31], v[136:137] op_sel_hi:[1,0,1]
	v_pk_fma_f32 v[68:69], v[20:21], v[30:31], v[126:127] op_sel_hi:[1,0,1]
	v_pk_fma_f32 v[24:25], v[62:63], v[34:35], v[24:25] op_sel_hi:[1,0,1]
	v_pk_fma_f32 v[32:33], v[64:65], v[38:39], v[28:29] op_sel_hi:[1,0,1]
	v_pk_fma_f32 v[30:31], v[22:23], v[26:27], v[128:129] op_sel_hi:[1,0,1]
	v_pk_fma_f32 v[28:29], v[20:21], v[26:27], v[130:131] op_sel_hi:[1,0,1]
	v_mov_b32_e32 v26, v27
	v_pk_fma_f32 v[24:25], v[66:67], v[38:39], v[24:25] op_sel_hi:[1,0,1]
	v_pk_fma_f32 v[22:23], v[22:23], v[26:27], v[132:133] op_sel_hi:[1,0,1]
	v_pk_fma_f32 v[20:21], v[20:21], v[26:27], v[134:135] op_sel_hi:[1,0,1]
	v_mov_b32_e32 v26, v35
	v_pk_fma_f32 v[24:25], v[54:55], v[26:27], v[24:25] op_sel_hi:[1,0,1]
	v_pk_fma_f32 v[32:33], v[52:53], v[26:27], v[32:33] op_sel_hi:[1,0,1]
	v_mov_b32_e32 v34, v39
	v_pk_fma_f32 v[26:27], v[58:59], v[34:35], v[24:25] op_sel_hi:[1,0,1]
	v_pk_fma_f32 v[24:25], v[56:57], v[34:35], v[32:33] op_sel_hi:[1,0,1]
	v_lshlrev_b32_e32 v32, 7, v119
	v_ashrrev_i32_e32 v33, 31, v32
	v_lshl_add_u64 v[32:33], v[32:33], 2, v[104:105]
	global_store_dwordx4 v[32:33], v[24:27], off nt
	s_nop 1
	v_lshl_add_u32 v24, v100, 12, v118
	ds_write_b128 v24, v[40:43] offset:16640
	ds_write_b128 v24, v[48:51] offset:17152
	ds_write_b128 v24, v[68:71] offset:17664
	ds_write_b128 v24, v[28:31] offset:18176
	ds_write_b128 v24, v[44:47] offset:18688
	ds_write_b128 v24, v[76:79] offset:19200
	ds_write_b128 v24, v[72:75] offset:19712
	ds_write_b128 v24, v[20:23] offset:20224
	v_add_u32_e32 v20, 1, v96
	v_cvt_f32_i32_e32 v20, v20
	v_add_u32_e32 v29, v113, v98
	s_waitcnt lgkmcnt(0)
	s_barrier
	v_mul_f32_e32 v20, v85, v20
	v_exp_f32_e32 v28, v20
	v_add_u32_e32 v20, 0x4100, v29
	ds_read2st64_b32 v[30:31], v29 offset0:65 offset1:66
	ds_read2st64_b32 v[32:33], v29 offset0:81 offset1:82
	ds_read2st64_b32 v[34:35], v29 offset0:97 offset1:98
	ds_read2st64_b32 v[36:37], v29 offset0:113 offset1:114
	ds_read2st64_b32 v[38:39], v29 offset0:129 offset1:130
	ds_read2st64_b32 v[40:41], v29 offset0:145 offset1:146
	ds_read2st64_b32 v[42:43], v29 offset0:161 offset1:162
	ds_read2st64_b32 v[44:45], v29 offset0:177 offset1:178
	ds_read2st64_b32 v[46:47], v29 offset0:193 offset1:194
	ds_read2st64_b32 v[48:49], v29 offset0:209 offset1:210
	ds_read2st64_b32 v[50:51], v29 offset0:225 offset1:226
	ds_read2st64_b32 v[52:53], v29 offset0:241 offset1:242
	ds_read2st64_b32 v[54:55], v20 offset0:192 offset1:208
	ds_read2st64_b32 v[56:57], v20 offset0:224 offset1:240
	s_waitcnt lgkmcnt(13)
	v_pk_add_f32 v[30:31], v[30:31], 0 op_sel_hi:[1,0]
	v_lshl_add_u32 v24, v96, 5, 0
	s_waitcnt lgkmcnt(12)
	v_pk_add_f32 v[30:31], v[30:31], v[32:33]
	v_add_u32_e32 v72, 0, v98
	s_waitcnt lgkmcnt(11)
	v_pk_add_f32 v[30:31], v[30:31], v[34:35]
	v_add_u32_e32 v29, 0x4200, v29
	s_waitcnt lgkmcnt(10)
	v_pk_add_f32 v[30:31], v[30:31], v[36:37]
	ds_read_b128 v[20:23], v24 offset:16384
	ds_read_b128 v[24:27], v24 offset:16400
	ds_read2st64_b32 v[58:59], v72 offset0:48 offset1:49
	ds_read2st64_b32 v[60:61], v72 offset0:50 offset1:51
	ds_read2st64_b32 v[62:63], v72 offset0:52 offset1:53
	ds_read2st64_b32 v[64:65], v72 offset0:54 offset1:55
	ds_read2st64_b32 v[66:67], v72 offset0:56 offset1:57
	ds_read2st64_b32 v[68:69], v72 offset0:58 offset1:59
	ds_read2st64_b32 v[70:71], v72 offset0:60 offset1:61
	ds_read2st64_b32 v[72:73], v72 offset0:62 offset1:63
	s_waitcnt lgkmcnt(14)
	v_pk_add_f32 v[30:31], v[30:31], v[38:39]
	ds_read2st64_b32 v[32:33], v29 offset0:192 offset1:208
	v_pk_add_f32 v[30:31], v[30:31], v[40:41]
	ds_read2st64_b32 v[36:37], v29 offset0:224 offset1:240
	v_pk_add_f32 v[30:31], v[30:31], v[42:43]
	s_waitcnt lgkmcnt(13)
	v_mov_b32_e32 v34, v54
	v_pk_add_f32 v[30:31], v[30:31], v[44:45]
	s_waitcnt lgkmcnt(1)
	v_mov_b32_e32 v35, v32
	v_pk_add_f32 v[30:31], v[30:31], v[46:47]
	v_mov_b32_e32 v32, v55
	v_pk_add_f32 v[30:31], v[30:31], v[48:49]
	s_nop 0
	v_pk_add_f32 v[30:31], v[30:31], v[50:51]
	s_nop 0
	v_pk_add_f32 v[30:31], v[30:31], v[52:53]
	s_nop 0
	v_pk_add_f32 v[30:31], v[30:31], v[34:35]
	s_nop 0
	v_pk_add_f32 v[30:31], v[30:31], v[32:33]
	v_mov_b32_e32 v32, v56
	s_waitcnt lgkmcnt(0)
	v_mov_b32_e32 v33, v36
	v_pk_add_f32 v[30:31], v[30:31], v[32:33]
	v_mov_b32_e32 v36, v57
	v_pk_add_f32 v[30:31], v[30:31], v[36:37]
	v_pk_mul_f32 v[32:33], v[20:21], v[58:59] op_sel_hi:[0,1]
	v_pk_fma_f32 v[28:29], v[28:29], v[30:31], v[32:33] op_sel_hi:[0,1,1]
	v_pk_fma_f32 v[20:21], v[20:21], v[60:61], v[28:29] op_sel:[1,0,0]
	s_nop 0
	v_pk_fma_f32 v[20:21], v[22:23], v[62:63], v[20:21] op_sel_hi:[0,1,1]
	v_mov_b32_e32 v22, v23
	v_pk_fma_f32 v[20:21], v[22:23], v[64:65], v[20:21] op_sel_hi:[0,1,1]
	v_pk_fma_f32 v[20:21], v[24:25], v[66:67], v[20:21] op_sel_hi:[0,1,1]
	v_pk_fma_f32 v[20:21], v[24:25], v[68:69], v[20:21] op_sel:[1,0,0]
	v_mov_b32_e32 v22, v27
	v_pk_fma_f32 v[20:21], v[26:27], v[70:71], v[20:21] op_sel_hi:[0,1,1]
	v_pk_fma_f32 v[20:21], v[22:23], v[72:73], v[20:21] op_sel_hi:[0,1,1]
	v_pk_mul_f32 v[22:23], v[20:21], v[20:21]
	v_lshlrev_b32_e32 v24, 16, v112
	v_add_f32_e32 v22, v22, v23
	v_xor_b32_e32 v23, 32, v228
	v_cmp_lt_i32_e32 vcc, v23, v115
	v_mul_f32_e32 v25, 0xbfb8aa3b, v24
	v_exp_f32_e32 v25, v25
	v_cndmask_b32_e32 v23, v228, v23, vcc
	v_lshlrev_b32_e32 v23, 2, v23
	ds_bpermute_b32 v23, v23, v22
	s_waitcnt lgkmcnt(0)
	v_add_f32_e32 v22, v22, v23
	v_xor_b32_e32 v23, 16, v228
	v_cmp_lt_i32_e32 vcc, v23, v115
	s_nop 1
	v_cndmask_b32_e32 v23, v228, v23, vcc
	v_lshlrev_b32_e32 v23, 2, v23
	ds_bpermute_b32 v23, v23, v22
	s_waitcnt lgkmcnt(0)
	v_add_f32_e32 v22, v22, v23
	v_xor_b32_e32 v23, 8, v228
	v_cmp_lt_i32_e32 vcc, v23, v115
	s_nop 1
	v_cndmask_b32_e32 v23, v228, v23, vcc
	v_lshlrev_b32_e32 v23, 2, v23
	ds_bpermute_b32 v23, v23, v22
	s_waitcnt lgkmcnt(0)
	v_add_f32_e32 v22, v22, v23
	ds_bpermute_b32 v23, v117, v22
	s_waitcnt lgkmcnt(0)
	v_add_f32_e32 v22, v22, v23
	ds_bpermute_b32 v23, v116, v22
	s_waitcnt lgkmcnt(0)
	v_add_f32_e32 v22, v22, v23
	ds_bpermute_b32 v23, v114, v22
	s_waitcnt lgkmcnt(0)
	v_add_f32_e32 v22, v22, v23
	v_fmamk_f32 v22, v22, 0x3c000000, v227
	v_mul_f32_e32 v23, 0x4b800000, v22
	v_cmp_gt_f32_e32 vcc, s15, v22
	s_nop 1
	v_cndmask_b32_e32 v22, v22, v23, vcc
	v_rsq_f32_e32 v22, v22
	v_add_f32_e32 v23, 1.0, v25
	v_rcp_f32_e32 v23, v23
	v_mul_f32_e32 v25, 0x45800000, v22
	v_cndmask_b32_e32 v25, v22, v25, vcc
	v_mul_f32_e32 v22, v23, v24
	v_lshlrev_b32_e32 v24, 16, v95
	v_mul_f32_e32 v26, 0xbfb8aa3b, v24
	v_exp_f32_e32 v26, v26
	v_mul_f32_e32 v20, v20, v25
	v_mul_f32_e32 v20, v22, v20
	v_bfe_u32 v22, v20, 16, 1
	v_add_f32_e32 v26, 1.0, v26
	v_add3_u32 v20, v20, v22, s76
	v_lshlrev_b64 v[22:23], 11, v[90:91]
	v_rcp_f32_e32 v26, v26
	v_lshl_add_u64 v[22:23], s[20:21], 0, v[22:23]
	v_lshl_add_u64 v[22:23], v[22:23], 0, s[22:23]
	v_mov_b32_e32 v95, v197
	v_lshl_add_u64 v[28:29], v[22:23], 0, v[94:95]
	global_store_short_d16_hi v[28:29], v20, off offset:1024
	v_mul_f32_e32 v20, v21, v25
	v_mul_f32_e32 v21, v26, v24
	v_mul_f32_e32 v30, v21, v20
	v_lshlrev_b32_e32 v20, 9, v111
	v_lshlrev_b32_e32 v21, 5, v89
	v_add3_u32 v32, s79, v20, v21
	v_bfe_u32 v31, v30, 16, 1
	ds_read_b128 v[20:23], v32
	ds_read_b128 v[24:27], v32 offset:16
	v_add3_u32 v30, v30, v31, s76
	global_store_short_d16_hi v[28:29], v30, off offset:1152
	s_waitcnt lgkmcnt(1)
	v_cvt_pk_bf16_f32 v20, v20, v21
	v_cvt_pk_bf16_f32 v21, v22, v23
	s_waitcnt lgkmcnt(0)
	v_cvt_pk_bf16_f32 v22, v24, v25
	v_cvt_pk_bf16_f32 v23, v26, v27
	ds_read_b128 v[24:27], v32 offset:128
	ds_read_b128 v[28:31], v32 offset:144
	v_mfma_f32_16x16x32_bf16 v[16:19], v[16:19], v[20:23], 0
	s_waitcnt lgkmcnt(1)
	v_cvt_pk_bf16_f32 v20, v24, v25
	v_cvt_pk_bf16_f32 v21, v26, v27
	s_waitcnt lgkmcnt(0)
	v_cvt_pk_bf16_f32 v22, v28, v29
	v_cvt_pk_bf16_f32 v23, v30, v31
	ds_read_b128 v[24:27], v32 offset:256
	ds_read_b128 v[28:31], v32 offset:272
	v_mfma_f32_16x16x32_bf16 v[12:15], v[12:15], v[20:23], v[16:19]
	s_waitcnt lgkmcnt(1)
	v_cvt_pk_bf16_f32 v16, v24, v25
	v_cvt_pk_bf16_f32 v17, v26, v27
	s_waitcnt lgkmcnt(0)
	v_cvt_pk_bf16_f32 v18, v28, v29
	v_cvt_pk_bf16_f32 v19, v30, v31
	ds_read_b128 v[20:23], v32 offset:384
	ds_read_b128 v[24:27], v32 offset:400
	s_waitcnt vmcnt(12)
	v_mfma_f32_16x16x32_bf16 v[8:11], v[8:11], v[16:19], v[12:15]
	s_waitcnt lgkmcnt(1)
	v_cvt_pk_bf16_f32 v12, v20, v21
	v_cvt_pk_bf16_f32 v13, v22, v23
	s_waitcnt lgkmcnt(0)
	v_cvt_pk_bf16_f32 v14, v24, v25
	v_cvt_pk_bf16_f32 v15, v26, v27
	s_waitcnt vmcnt(11)
	v_mfma_f32_16x16x32_bf16 v[4:7], v[4:7], v[12:15], v[8:11]
	s_and_saveexec_b64 s[0:1], s[40:41]
	s_cbranch_execz .LBB0_671
	s_waitcnt vmcnt(10)
	s_nop 0
	v_and_b32_e32 v10, 0xffff0000, v92
	v_mov_b32_e32 v17, v0
	v_mul_f32_e32 v0, 0xbfb8aa3b, v10
	v_exp_f32_e32 v0, v0
	v_lshlrev_b32_e32 v8, 16, v92
	v_mul_f32_e32 v9, 0xbfb8aa3b, v8
	v_exp_f32_e32 v9, v9
	v_add_f32_e32 v0, 1.0, v0
	v_rcp_f32_e32 v0, v0
	v_mov_b32_e32 v11, v5
	v_lshlrev_b32_e32 v12, 16, v93
	v_and_b32_e32 v14, 0xffff0000, v93
	v_add_f32_e32 v9, 1.0, v9
	v_pk_mul_f32 v[0:1], v[0:1], v[10:11]
	v_rcp_f32_e32 v16, v9
	v_mul_f32_e32 v0, v0, v1
	v_mul_f32_e32 v1, 0xbfb8aa3b, v12
	v_mov_b32_e32 v5, v2
	v_mul_f32_e32 v2, 0xbfb8aa3b, v14
	v_exp_f32_e32 v1, v1
	v_exp_f32_e32 v2, v2
	v_mov_b32_e32 v9, v4
	v_pk_mul_f32 v[8:9], v[16:17], v[8:9]
	v_add_f32_e32 v1, 1.0, v1
	v_mul_f32_e32 v4, v8, v9
	v_add_f32_e32 v2, 1.0, v2
	v_cvt_pk_bf16_f32 v0, v4, v0
	v_rcp_f32_e32 v4, v1
	v_rcp_f32_e32 v2, v2
	v_mov_b32_e32 v13, v6
	v_mov_b32_e32 v15, v7
	v_pk_mul_f32 v[4:5], v[4:5], v[12:13]
	v_pk_mul_f32 v[2:3], v[2:3], v[14:15]
	v_mul_f32_e32 v1, v4, v5
	v_mul_f32_e32 v2, v2, v3
	v_mov_b32_e32 v89, s13
	v_cvt_pk_bf16_f32 v1, v1, v2
	v_lshlrev_b64 v[2:3], 11, v[88:89]
	v_lshl_add_u64 v[2:3], s[20:21], 0, v[2:3]
	v_lshl_add_u64 v[2:3], v[86:87], 1, v[2:3]
	global_store_dwordx2 v[2:3], v[0:1], off
	s_branch .LBB0_671
